# final epilogue part 1: row sum atomics issued together at the end instead of one per row
# baseline (speedup 1.0000x reference)
.LBB0_2191:
	s_lshl_b32 s28, s60, 8
	s_add_i32 s26, s28, 0xffffe000
	s_ashr_i32 s26, s26, 12
	s_add_i32 s26, s26, 1
	s_cmp_gt_i32 s60, 31
	s_cselect_b32 s26, s26, 0
	s_mul_hi_i32 s27, s26, 0x12000
	s_mul_i32 s26, s26, 0x12000
	v_readlane_b32 s30, v243, 42
	v_readlane_b32 s31, v243, 43
	s_add_u32 s26, s30, s26
	s_addc_u32 s27, s31, s27
	s_lshl_b32 s29, s61, 8
	v_mov_b32_e32 v160, v173
	v_mov_b32_e32 v182, v175
	s_or_b32 s29, s29, s48
	s_add_i32 s28, s28, s47
	v_lshl_add_u32 v142, v182, 3, s29
	v_ashrrev_i32_e32 v143, 31, v142
	v_lshlrev_b64 v[140:141], 2, v[142:143]
	v_add_u32_e32 v160, s28, v160
	v_lshl_add_u64 v[144:145], s[26:27], 0, v[140:141]
	v_ashrrev_i32_e32 v161, 31, v160
	v_lshl_add_u64 v[156:157], v[144:145], 0, s[18:19]
	v_add_co_u32_e32 v144, vcc, s44, v144
	v_lshlrev_b64 v[162:163], 13, v[160:161]
	s_nop 0
	v_addc_co_u32_e32 v145, vcc, 0, v145, vcc
	v_lshl_add_u64 v[162:163], s[90:91], 0, v[162:163]
	global_load_dwordx4 v[144:147], v[144:145], off
	s_nop 0
	global_load_dwordx4 v[148:151], v[156:157], off offset:528
	global_load_dwordx4 v[152:155], v[156:157], off offset:16
	s_nop 0
	global_load_dwordx4 v[156:159], v[156:157], off offset:512
	v_lshl_add_u64 v[140:141], v[162:163], 0, v[140:141]
	global_load_dwordx4 v[192:195], v[140:141], off
	global_load_dwordx4 v[196:199], v[140:141], off offset:16
	global_load_dwordx4 v[200:203], v[140:141], off offset:512
	global_load_dwordx4 v[204:207], v[140:141], off offset:528
	v_and_b32_e32 v163, 64, v188
	v_xor_b32_e32 v162, 16, v188
	v_add_u32_e32 v183, 64, v163
	v_cmp_lt_i32_e32 vcc, v162, v183
	s_waitcnt vmcnt(0)
	v_pk_mul_f32 v[176:177], v[146:147], 0.5 op_sel_hi:[1,0]
	v_cndmask_b32_e32 v162, v188, v162, vcc
	v_lshlrev_b32_e32 v190, 2, v162
	v_pk_mul_f32 v[180:181], v[144:145], 0.5 op_sel_hi:[1,0]
	v_pk_mul_f32 v[170:171], v[154:155], 0.5 op_sel_hi:[1,0]
	v_pk_mul_f32 v[178:179], v[152:153], 0.5 op_sel_hi:[1,0]
	v_pk_mul_f32 v[166:167], v[158:159], 0.5 op_sel_hi:[1,0]
	v_pk_mul_f32 v[168:169], v[156:157], 0.5 op_sel_hi:[1,0]
	v_pk_mul_f32 v[162:163], v[150:151], 0.5 op_sel_hi:[1,0]
	v_pk_mul_f32 v[164:165], v[148:149], 0.5 op_sel_hi:[1,0]
	v_pk_fma_f32 v[144:145], v[126:127], v[176:177], v[194:195]
	v_pk_fma_f32 v[146:147], v[124:125], v[180:181], v[192:193]
	v_pk_fma_f32 v[124:125], v[122:123], v[170:171], v[198:199]
	v_pk_fma_f32 v[126:127], v[120:121], v[178:179], v[196:197]
	v_pk_fma_f32 v[120:121], v[118:119], v[166:167], v[202:203]
	v_pk_fma_f32 v[122:123], v[116:117], v[168:169], v[200:201]
	v_pk_fma_f32 v[116:117], v[114:115], v[162:163], v[206:207]
	v_pk_fma_f32 v[118:119], v[112:113], v[164:165], v[204:205]
	v_mul_f32_e32 v112, v147, v147
	v_mul_f32_e32 v113, v145, v145
	v_mul_f32_e32 v114, v127, v127
	v_mul_f32_e32 v115, v125, v125
	v_mul_f32_e32 v148, v123, v123
	v_mul_f32_e32 v149, v121, v121
	v_mul_f32_e32 v150, v119, v119
	v_mul_f32_e32 v151, v117, v117
	v_fmac_f32_e32 v112, v146, v146
	v_fmac_f32_e32 v113, v144, v144
	v_fmac_f32_e32 v114, v126, v126
	v_fmac_f32_e32 v115, v124, v124
	v_fmac_f32_e32 v148, v122, v122
	v_fmac_f32_e32 v149, v120, v120
	v_fmac_f32_e32 v150, v118, v118
	v_fmac_f32_e32 v151, v116, v116
	v_add_f32_e32 v112, v112, v113
	v_add_f32_e32 v113, v114, v115
	v_add_f32_e32 v114, v148, v149
	v_add_f32_e32 v115, v150, v151
	v_add_f32_e32 v112, v112, v113
	v_add_f32_e32 v113, v114, v115
	v_add_f32_e32 v112, v112, v113
	ds_bpermute_b32 v113, v190, v112
	v_xor_b32_e32 v114, 32, v188
	v_cmp_lt_i32_e32 vcc, v114, v183
	s_nop 1
	v_cndmask_b32_e32 v114, v188, v114, vcc
	v_lshlrev_b32_e32 v191, 2, v114
	s_waitcnt lgkmcnt(0)
	v_add_f32_e32 v114, v112, v113
	ds_bpermute_b32 v115, v191, v114
	v_cmp_eq_u32_e32 vcc, 0, v182
	v_lshl_add_u64 v[112:113], v[160:161], 2, s[8:9]
	s_and_saveexec_b64 s[26:27], vcc
	s_cbranch_execz .LBB0_2193
	s_waitcnt lgkmcnt(0)
	v_add_f32_e32 v114, v114, v115
	v_mov_b32_e32 v230, v114
	v_mov_b32_e32 v238, v112
	v_mov_b32_e32 v239, v113
.LBB0_2193:
	s_or_b64 exec, exec, s[26:27]
	v_add_u32_e32 v150, 16, v160
	v_ashrrev_i32_e32 v151, 31, v150
	s_waitcnt lgkmcnt(0)
	v_lshlrev_b64 v[114:115], 13, v[150:151]
	v_lshl_add_u64 v[114:115], s[90:91], 0, v[114:115]
	v_lshl_add_u64 v[114:115], v[142:143], 2, v[114:115]
	global_load_dwordx4 v[152:155], v[114:115], off
	global_load_dwordx4 v[156:159], v[114:115], off offset:16
	global_load_dwordx4 v[192:195], v[114:115], off offset:512
	global_load_dwordx4 v[196:199], v[114:115], off offset:528
	s_waitcnt vmcnt(3)
	v_pk_fma_f32 v[110:111], v[110:111], v[176:177], v[154:155]
	v_pk_fma_f32 v[148:149], v[108:109], v[180:181], v[152:153]
	s_waitcnt vmcnt(2)
	v_pk_fma_f32 v[106:107], v[106:107], v[170:171], v[158:159]
	v_pk_fma_f32 v[108:109], v[104:105], v[178:179], v[156:157]
	s_waitcnt vmcnt(1)
	v_pk_fma_f32 v[102:103], v[102:103], v[166:167], v[194:195]
	v_pk_fma_f32 v[104:105], v[100:101], v[168:169], v[192:193]
	s_waitcnt vmcnt(0)
	v_pk_fma_f32 v[98:99], v[98:99], v[162:163], v[198:199]
	v_pk_fma_f32 v[100:101], v[96:97], v[164:165], v[196:197]
	v_mul_f32_e32 v96, v149, v149
	v_mul_f32_e32 v97, v111, v111
	v_mul_f32_e32 v152, v109, v109
	v_mul_f32_e32 v153, v107, v107
	v_mul_f32_e32 v154, v105, v105
	v_mul_f32_e32 v155, v103, v103
	v_mul_f32_e32 v156, v101, v101
	v_mul_f32_e32 v157, v99, v99
	v_fmac_f32_e32 v96, v148, v148
	v_fmac_f32_e32 v97, v110, v110
	v_fmac_f32_e32 v152, v108, v108
	v_fmac_f32_e32 v153, v106, v106
	v_fmac_f32_e32 v154, v104, v104
	v_fmac_f32_e32 v155, v102, v102
	v_fmac_f32_e32 v156, v100, v100
	v_fmac_f32_e32 v157, v98, v98
	v_add_f32_e32 v96, v96, v97
	v_add_f32_e32 v97, v152, v153
	v_add_f32_e32 v152, v154, v155
	v_add_f32_e32 v153, v156, v157
	v_add_f32_e32 v96, v96, v97
	v_add_f32_e32 v97, v152, v153
	v_add_f32_e32 v96, v96, v97
	ds_bpermute_b32 v97, v190, v96
	s_waitcnt lgkmcnt(0)
	v_add_f32_e32 v96, v96, v97
	ds_bpermute_b32 v97, v191, v96
	s_and_saveexec_b64 s[26:27], vcc
	s_cbranch_execz .LBB0_2195
	v_lshl_add_u64 v[150:151], v[150:151], 2, s[8:9]
	s_waitcnt lgkmcnt(0)
	v_add_f32_e32 v96, v96, v97
	v_mov_b32_e32 v231, v96
.LBB0_2195:
	s_or_b64 exec, exec, s[26:27]
	v_add_u32_e32 v152, 32, v160
	v_ashrrev_i32_e32 v153, 31, v152
	s_waitcnt lgkmcnt(0)
	v_lshlrev_b64 v[96:97], 13, v[152:153]
	v_lshl_add_u64 v[96:97], s[90:91], 0, v[96:97]
	v_lshl_add_u64 v[96:97], v[142:143], 2, v[96:97]
	global_load_dwordx4 v[154:157], v[96:97], off
	global_load_dwordx4 v[192:195], v[96:97], off offset:16
	global_load_dwordx4 v[196:199], v[96:97], off offset:512
	global_load_dwordx4 v[200:203], v[96:97], off offset:528
	s_waitcnt vmcnt(3)
	v_pk_fma_f32 v[94:95], v[94:95], v[176:177], v[156:157]
	v_pk_fma_f32 v[150:151], v[92:93], v[180:181], v[154:155]
	s_waitcnt vmcnt(2)
	v_pk_fma_f32 v[90:91], v[90:91], v[170:171], v[194:195]
	v_pk_fma_f32 v[92:93], v[88:89], v[178:179], v[192:193]
	s_waitcnt vmcnt(1)
	v_pk_fma_f32 v[86:87], v[86:87], v[166:167], v[198:199]
	v_pk_fma_f32 v[88:89], v[84:85], v[168:169], v[196:197]
	s_waitcnt vmcnt(0)
	v_pk_fma_f32 v[82:83], v[82:83], v[162:163], v[202:203]
	v_pk_fma_f32 v[84:85], v[80:81], v[164:165], v[200:201]
	v_mul_f32_e32 v80, v151, v151
	v_mul_f32_e32 v81, v95, v95
	v_mul_f32_e32 v154, v93, v93
	v_mul_f32_e32 v155, v91, v91
	v_mul_f32_e32 v156, v89, v89
	v_mul_f32_e32 v157, v87, v87
	v_mul_f32_e32 v158, v85, v85
	v_mul_f32_e32 v159, v83, v83
	v_fmac_f32_e32 v80, v150, v150
	v_fmac_f32_e32 v81, v94, v94
	v_fmac_f32_e32 v154, v92, v92
	v_fmac_f32_e32 v155, v90, v90
	v_fmac_f32_e32 v156, v88, v88
	v_fmac_f32_e32 v157, v86, v86
	v_fmac_f32_e32 v158, v84, v84
	v_fmac_f32_e32 v159, v82, v82
	v_add_f32_e32 v80, v80, v81
	v_add_f32_e32 v81, v154, v155
	v_add_f32_e32 v154, v156, v157
	v_add_f32_e32 v155, v158, v159
	v_add_f32_e32 v80, v80, v81
	v_add_f32_e32 v81, v154, v155
	v_add_f32_e32 v80, v80, v81
	ds_bpermute_b32 v81, v190, v80
	s_waitcnt lgkmcnt(0)
	v_add_f32_e32 v80, v80, v81
	ds_bpermute_b32 v81, v191, v80
	s_and_saveexec_b64 s[26:27], vcc
	s_cbranch_execz .LBB0_2197
	v_lshl_add_u64 v[152:153], v[152:153], 2, s[8:9]
	s_waitcnt lgkmcnt(0)
	v_add_f32_e32 v80, v80, v81
	v_mov_b32_e32 v232, v80
.LBB0_2197:
	s_or_b64 exec, exec, s[26:27]
	v_add_u32_e32 v154, 48, v160
	v_ashrrev_i32_e32 v155, 31, v154
	s_waitcnt lgkmcnt(0)
	v_lshlrev_b64 v[80:81], 13, v[154:155]
	v_lshl_add_u64 v[80:81], s[90:91], 0, v[80:81]
	v_lshl_add_u64 v[80:81], v[142:143], 2, v[80:81]
	global_load_dwordx4 v[156:159], v[80:81], off
	global_load_dwordx4 v[192:195], v[80:81], off offset:16
	global_load_dwordx4 v[196:199], v[80:81], off offset:512
	global_load_dwordx4 v[200:203], v[80:81], off offset:528
	s_waitcnt vmcnt(3)
	v_pk_fma_f32 v[78:79], v[78:79], v[176:177], v[158:159]
	v_pk_fma_f32 v[152:153], v[76:77], v[180:181], v[156:157]
	s_waitcnt vmcnt(2)
	v_pk_fma_f32 v[74:75], v[74:75], v[170:171], v[194:195]
	v_pk_fma_f32 v[76:77], v[72:73], v[178:179], v[192:193]
	s_waitcnt vmcnt(1)
	v_pk_fma_f32 v[70:71], v[70:71], v[166:167], v[198:199]
	v_pk_fma_f32 v[72:73], v[68:69], v[168:169], v[196:197]
	s_waitcnt vmcnt(0)
	v_pk_fma_f32 v[66:67], v[66:67], v[162:163], v[202:203]
	v_pk_fma_f32 v[68:69], v[64:65], v[164:165], v[200:201]
	v_mul_f32_e32 v64, v153, v153
	v_mul_f32_e32 v65, v79, v79
	v_mul_f32_e32 v156, v77, v77
	v_mul_f32_e32 v157, v75, v75
	v_mul_f32_e32 v158, v73, v73
	v_mul_f32_e32 v159, v71, v71
	v_mul_f32_e32 v161, v69, v69
	v_mul_f32_e32 v182, v67, v67
	v_fmac_f32_e32 v64, v152, v152
	v_fmac_f32_e32 v65, v78, v78
	v_fmac_f32_e32 v156, v76, v76
	v_fmac_f32_e32 v157, v74, v74
	v_fmac_f32_e32 v158, v72, v72
	v_fmac_f32_e32 v159, v70, v70
	v_fmac_f32_e32 v161, v68, v68
	v_fmac_f32_e32 v182, v66, v66
	v_add_f32_e32 v64, v64, v65
	v_add_f32_e32 v65, v156, v157
	v_add_f32_e32 v156, v158, v159
	v_add_f32_e32 v157, v161, v182
	v_add_f32_e32 v64, v64, v65
	v_add_f32_e32 v65, v156, v157
	v_add_f32_e32 v64, v64, v65
	ds_bpermute_b32 v65, v190, v64
	s_waitcnt lgkmcnt(0)
	v_add_f32_e32 v64, v64, v65
	ds_bpermute_b32 v65, v191, v64
	s_and_saveexec_b64 s[26:27], vcc
	s_cbranch_execz .LBB0_2199
	v_lshl_add_u64 v[154:155], v[154:155], 2, s[8:9]
	s_waitcnt lgkmcnt(0)
	v_add_f32_e32 v64, v64, v65
	v_mov_b32_e32 v233, v64
.LBB0_2199:
	s_or_b64 exec, exec, s[26:27]
	v_add_u32_e32 v156, 0x80, v160
	v_ashrrev_i32_e32 v157, 31, v156
	s_waitcnt lgkmcnt(0)
	v_lshlrev_b64 v[64:65], 13, v[156:157]
	v_lshl_add_u64 v[64:65], s[90:91], 0, v[64:65]
	v_lshl_add_u64 v[64:65], v[142:143], 2, v[64:65]
	global_load_dwordx4 v[192:195], v[64:65], off
	global_load_dwordx4 v[196:199], v[64:65], off offset:16
	global_load_dwordx4 v[200:203], v[64:65], off offset:512
	global_load_dwordx4 v[204:207], v[64:65], off offset:528
	s_waitcnt vmcnt(3)
	v_pk_fma_f32 v[62:63], v[62:63], v[176:177], v[194:195]
	v_pk_fma_f32 v[154:155], v[60:61], v[180:181], v[192:193]
	s_waitcnt vmcnt(2)
	v_pk_fma_f32 v[58:59], v[58:59], v[170:171], v[198:199]
	v_pk_fma_f32 v[60:61], v[56:57], v[178:179], v[196:197]
	s_waitcnt vmcnt(1)
	v_pk_fma_f32 v[54:55], v[54:55], v[166:167], v[202:203]
	v_pk_fma_f32 v[56:57], v[52:53], v[168:169], v[200:201]
	s_waitcnt vmcnt(0)
	v_pk_fma_f32 v[50:51], v[50:51], v[162:163], v[206:207]
	v_pk_fma_f32 v[52:53], v[48:49], v[164:165], v[204:205]
	v_mul_f32_e32 v48, v155, v155
	v_mul_f32_e32 v49, v63, v63
	v_mul_f32_e32 v158, v61, v61
	v_mul_f32_e32 v159, v59, v59
	v_mul_f32_e32 v161, v57, v57
	v_mul_f32_e32 v182, v55, v55
	v_mul_f32_e32 v183, v53, v53
	v_mul_f32_e32 v192, v51, v51
	v_fmac_f32_e32 v48, v154, v154
	v_fmac_f32_e32 v49, v62, v62
	v_fmac_f32_e32 v158, v60, v60
	v_fmac_f32_e32 v159, v58, v58
	v_fmac_f32_e32 v161, v56, v56
	v_fmac_f32_e32 v182, v54, v54
	v_fmac_f32_e32 v183, v52, v52
	v_fmac_f32_e32 v192, v50, v50
	v_add_f32_e32 v48, v48, v49
	v_add_f32_e32 v49, v158, v159
	v_add_f32_e32 v158, v161, v182
	v_add_f32_e32 v159, v183, v192
	v_add_f32_e32 v48, v48, v49
	v_add_f32_e32 v49, v158, v159
	v_add_f32_e32 v48, v48, v49
	ds_bpermute_b32 v49, v190, v48
	s_waitcnt lgkmcnt(0)
	v_add_f32_e32 v48, v48, v49
	ds_bpermute_b32 v49, v191, v48
	s_and_saveexec_b64 s[26:27], vcc
	s_cbranch_execz .LBB0_2201
	v_lshl_add_u64 v[156:157], v[156:157], 2, s[8:9]
	s_waitcnt lgkmcnt(0)
	v_add_f32_e32 v48, v48, v49
	v_mov_b32_e32 v234, v48
.LBB0_2201:
	s_or_b64 exec, exec, s[26:27]
	v_add_u32_e32 v158, 0x90, v160
	v_ashrrev_i32_e32 v159, 31, v158
	s_waitcnt lgkmcnt(0)
	v_lshlrev_b64 v[48:49], 13, v[158:159]
	v_lshl_add_u64 v[48:49], s[90:91], 0, v[48:49]
	v_lshl_add_u64 v[48:49], v[142:143], 2, v[48:49]
	global_load_dwordx4 v[192:195], v[48:49], off
	global_load_dwordx4 v[196:199], v[48:49], off offset:16
	global_load_dwordx4 v[200:203], v[48:49], off offset:512
	global_load_dwordx4 v[204:207], v[48:49], off offset:528
	s_waitcnt vmcnt(3)
	v_pk_fma_f32 v[46:47], v[46:47], v[176:177], v[194:195]
	v_pk_fma_f32 v[156:157], v[44:45], v[180:181], v[192:193]
	s_waitcnt vmcnt(2)
	v_pk_fma_f32 v[42:43], v[42:43], v[170:171], v[198:199]
	v_pk_fma_f32 v[44:45], v[40:41], v[178:179], v[196:197]
	s_waitcnt vmcnt(1)
	v_pk_fma_f32 v[38:39], v[38:39], v[166:167], v[202:203]
	v_pk_fma_f32 v[40:41], v[36:37], v[168:169], v[200:201]
	s_waitcnt vmcnt(0)
	v_pk_fma_f32 v[34:35], v[34:35], v[162:163], v[206:207]
	v_pk_fma_f32 v[36:37], v[32:33], v[164:165], v[204:205]
	v_mul_f32_e32 v32, v157, v157
	v_mul_f32_e32 v33, v47, v47
	v_mul_f32_e32 v161, v45, v45
	v_mul_f32_e32 v182, v43, v43
	v_mul_f32_e32 v183, v41, v41
	v_mul_f32_e32 v192, v39, v39
	v_mul_f32_e32 v193, v37, v37
	v_mul_f32_e32 v194, v35, v35
	v_fmac_f32_e32 v32, v156, v156
	v_fmac_f32_e32 v33, v46, v46
	v_fmac_f32_e32 v161, v44, v44
	v_fmac_f32_e32 v182, v42, v42
	v_fmac_f32_e32 v183, v40, v40
	v_fmac_f32_e32 v192, v38, v38
	v_fmac_f32_e32 v193, v36, v36
	v_fmac_f32_e32 v194, v34, v34
	v_add_f32_e32 v32, v32, v33
	v_add_f32_e32 v33, v161, v182
	v_add_f32_e32 v161, v183, v192
	v_add_f32_e32 v182, v193, v194
	v_add_f32_e32 v32, v32, v33
	v_add_f32_e32 v33, v161, v182
	v_add_f32_e32 v32, v32, v33
	ds_bpermute_b32 v33, v190, v32
	s_waitcnt lgkmcnt(0)
	v_add_f32_e32 v32, v32, v33
	ds_bpermute_b32 v33, v191, v32
	s_and_saveexec_b64 s[26:27], vcc
	s_cbranch_execz .LBB0_2203
	v_lshl_add_u64 v[158:159], v[158:159], 2, s[8:9]
	s_waitcnt lgkmcnt(0)
	v_add_f32_e32 v32, v32, v33
	v_mov_b32_e32 v235, v32
.LBB0_2203:
	s_or_b64 exec, exec, s[26:27]
	v_add_u32_e32 v182, 0xa0, v160
	v_ashrrev_i32_e32 v183, 31, v182
	s_waitcnt lgkmcnt(0)
	v_lshlrev_b64 v[32:33], 13, v[182:183]
	v_lshl_add_u64 v[32:33], s[90:91], 0, v[32:33]
	v_lshl_add_u64 v[32:33], v[142:143], 2, v[32:33]
	global_load_dwordx4 v[192:195], v[32:33], off
	global_load_dwordx4 v[196:199], v[32:33], off offset:16
	global_load_dwordx4 v[200:203], v[32:33], off offset:512
	global_load_dwordx4 v[204:207], v[32:33], off offset:528
	s_waitcnt vmcnt(3)
	v_pk_fma_f32 v[30:31], v[30:31], v[176:177], v[194:195]
	v_pk_fma_f32 v[158:159], v[28:29], v[180:181], v[192:193]
	s_waitcnt vmcnt(2)
	v_pk_fma_f32 v[26:27], v[26:27], v[170:171], v[198:199]
	v_pk_fma_f32 v[28:29], v[24:25], v[178:179], v[196:197]
	s_waitcnt vmcnt(1)
	v_pk_fma_f32 v[22:23], v[22:23], v[166:167], v[202:203]
	v_pk_fma_f32 v[24:25], v[20:21], v[168:169], v[200:201]
	s_waitcnt vmcnt(0)
	v_pk_fma_f32 v[18:19], v[18:19], v[162:163], v[206:207]
	v_pk_fma_f32 v[20:21], v[16:17], v[164:165], v[204:205]
	v_mul_f32_e32 v16, v159, v159
	v_mul_f32_e32 v17, v31, v31
	v_mul_f32_e32 v161, v29, v29
	v_mul_f32_e32 v192, v27, v27
	v_mul_f32_e32 v193, v25, v25
	v_mul_f32_e32 v194, v23, v23
	v_mul_f32_e32 v195, v21, v21
	v_mul_f32_e32 v196, v19, v19
	v_fmac_f32_e32 v16, v158, v158
	v_fmac_f32_e32 v17, v30, v30
	v_fmac_f32_e32 v161, v28, v28
	v_fmac_f32_e32 v192, v26, v26
	v_fmac_f32_e32 v193, v24, v24
	v_fmac_f32_e32 v194, v22, v22
	v_fmac_f32_e32 v195, v20, v20
	v_fmac_f32_e32 v196, v18, v18
	v_add_f32_e32 v16, v16, v17
	v_add_f32_e32 v17, v161, v192
	v_add_f32_e32 v161, v193, v194
	v_add_f32_e32 v192, v195, v196
	v_add_f32_e32 v16, v16, v17
	v_add_f32_e32 v17, v161, v192
	v_add_f32_e32 v16, v16, v17
	ds_bpermute_b32 v17, v190, v16
	s_waitcnt lgkmcnt(0)
	v_add_f32_e32 v16, v16, v17
	ds_bpermute_b32 v17, v191, v16
	s_and_saveexec_b64 s[26:27], vcc
	s_cbranch_execz .LBB0_2205
	v_lshl_add_u64 v[182:183], v[182:183], 2, s[8:9]
	s_waitcnt lgkmcnt(0)
	v_add_f32_e32 v16, v16, v17
	v_mov_b32_e32 v236, v16
.LBB0_2205:
	s_or_b64 exec, exec, s[26:27]
	v_add_u32_e32 v160, 0xb0, v160
	v_ashrrev_i32_e32 v161, 31, v160
	s_waitcnt lgkmcnt(0)
	v_lshlrev_b64 v[16:17], 13, v[160:161]
	v_lshl_add_u64 v[16:17], s[90:91], 0, v[16:17]
	v_lshl_add_u64 v[16:17], v[142:143], 2, v[16:17]
	global_load_dwordx4 v[192:195], v[16:17], off
	global_load_dwordx4 v[196:199], v[16:17], off offset:16
	global_load_dwordx4 v[200:203], v[16:17], off offset:512
	global_load_dwordx4 v[204:207], v[16:17], off offset:528
	s_waitcnt vmcnt(3)
	v_pk_fma_f32 v[14:15], v[14:15], v[176:177], v[194:195]
	v_pk_fma_f32 v[12:13], v[12:13], v[180:181], v[192:193]
	s_waitcnt vmcnt(2)
	v_pk_fma_f32 v[10:11], v[10:11], v[170:171], v[198:199]
	v_pk_fma_f32 v[8:9], v[8:9], v[178:179], v[196:197]
	s_waitcnt vmcnt(1)
	v_pk_fma_f32 v[6:7], v[6:7], v[166:167], v[202:203]
	v_pk_fma_f32 v[4:5], v[4:5], v[168:169], v[200:201]
	s_waitcnt vmcnt(0)
	v_pk_fma_f32 v[2:3], v[2:3], v[162:163], v[206:207]
	v_pk_fma_f32 v[0:1], v[0:1], v[164:165], v[204:205]
	v_mul_f32_e32 v162, v13, v13
	v_mul_f32_e32 v163, v15, v15
	v_mul_f32_e32 v164, v9, v9
	v_mul_f32_e32 v165, v11, v11
	v_mul_f32_e32 v166, v5, v5
	v_mul_f32_e32 v167, v7, v7
	v_mul_f32_e32 v168, v1, v1
	v_mul_f32_e32 v169, v3, v3
	v_fmac_f32_e32 v162, v12, v12
	v_fmac_f32_e32 v163, v14, v14
	v_fmac_f32_e32 v164, v8, v8
	v_fmac_f32_e32 v165, v10, v10
	v_fmac_f32_e32 v166, v4, v4
	v_fmac_f32_e32 v167, v6, v6
	v_fmac_f32_e32 v168, v0, v0
	v_fmac_f32_e32 v169, v2, v2
	v_add_f32_e32 v162, v162, v163
	v_add_f32_e32 v163, v164, v165
	v_add_f32_e32 v164, v166, v167
	v_add_f32_e32 v165, v168, v169
	v_add_f32_e32 v162, v162, v163
	v_add_f32_e32 v163, v164, v165
	v_add_f32_e32 v162, v162, v163
	ds_bpermute_b32 v163, v190, v162
	s_waitcnt lgkmcnt(0)
	v_add_f32_e32 v162, v162, v163
	ds_bpermute_b32 v163, v191, v162
	s_and_saveexec_b64 s[26:27], vcc
	s_cbranch_execz .LBB0_2207
	v_lshl_add_u64 v[160:161], v[160:161], 2, s[8:9]
	s_waitcnt lgkmcnt(0)
	v_add_f32_e32 v162, v162, v163
	v_mov_b32_e32 v237, v162
.LBB0_2207:
	s_or_b64 exec, exec, s[26:27]
	s_and_saveexec_b64 s[26:27], vcc
	global_atomic_add_f32 v[238:239], v230, off
	global_atomic_add_f32 v[238:239], v231, off offset:64
	global_atomic_add_f32 v[238:239], v232, off offset:128
	global_atomic_add_f32 v[238:239], v233, off offset:192
	global_atomic_add_f32 v[238:239], v234, off offset:512
	global_atomic_add_f32 v[238:239], v235, off offset:576
	global_atomic_add_f32 v[238:239], v236, off offset:640
	global_atomic_add_f32 v[238:239], v237, off offset:704
	s_or_b64 exec, exec, s[26:27]
	s_lshl_b32 s26, s60, 6
	s_ashr_i32 s27, s26, 31
	s_waitcnt vmcnt(0)
	s_lshl_b64 s[26:27], s[26:27], 2
	s_add_u32 s26, s45, s26
	s_addc_u32 s27, s46, s27
	s_and_saveexec_b64 s[28:29], s[0:1]
	s_cbranch_execz .LBB0_2210
	s_mov_b64 s[30:31], exec
	v_mbcnt_lo_u32_b32 v160, s30, 0
	v_mbcnt_hi_u32_b32 v160, s31, v160
	v_cmp_eq_u32_e32 vcc, 0, v160
	s_and_b64 s[60:61], exec, vcc
	s_mov_b64 exec, s[60:61]
	s_cbranch_execz .LBB0_2210
	s_bcnt1_i32_b64 s30, s[30:31]
	v_mov_b32_e32 v160, s30
	global_atomic_add v131, v160, s[26:27]
